# GEMM mainloops: per-segment s_setprio flips removed; one static s_setprio 1 for the leading half (waves 0-3) during GEMM phases
# speedup vs baseline: 1.0127x; 1.0127x over previous
; #define PG8_STAGE(bufoff, gbase, voff) do { _Pragma("unroll") for (int _i = 0; _i < 2; ++_i) \
;         __builtin_amdgcn_global_load_lds((const unsigned*)((const char*)(gbase) + (voff)[_i]), (PG8_LAS unsigned*)(lds + (bufoff) + ldsw + _i * 8192), 16, 0, 0); } while (0)
; #define PG8_BAR __builtin_amdgcn_s_barrier()
; template <class Epi, class Sched, bool ALIGN_EPI = false, bool SP2 = false>
; __device__ __forceinline__ void gemm_phase(PG8_LAS unsigned char* lds, const Gemm g, const Sched& S, const Epi& E) {
;     ...
;     const int tid = tid_, wid = __builtin_amdgcn_readfirstlane(tid >> 6), lane = tid & 63, wr = wid >> 2, wc = wid & 3, fr = lane & 15, fq = lane >> 4;
;     const int K = g.K, nt = K / BK;
;     unsigned voffA[2], voffB[2];
; #pragma unroll
;     for (int i = 0; i < 2; ++i) { int R, C; stage_rc(tid * 16 + i * 8192, R, C); const int Rb = Epi::PERM ? ((R & ~31) + perm32(R & 31)) : R;
;         voffA[i] = (unsigned)(R * K + C) * 2u; voffB[i] = (unsigned)(Rb * K + C) * 2u; }
;     ...
;     const char* cA = (const char*)g.A + (size_t)cur.pm * tstep; const char* cB = (const char*)g.Bt + (size_t)cur.pn * tstep;
;     S.a_ready(cur);
;     if constexpr (SP2) {
;         PG8_STAGE(PG8_SB(0, 0), cB, voffB); PG8_STAGE(PG8_SB(0, 1), cB + hstep, voffB); PG8_STAGE(PG8_SA(0, 0), cA, voffA); PG8_STAGE(PG8_SA(0, 1), cA + hstep, voffA);
;         if (wr == 1) PG8_BAR;
.LBB0_228:
	s_waitcnt lgkmcnt(0)
	v_mov_b32_e32 v14, v230
	s_waitcnt lgkmcnt(0)
	s_barrier
	s_cmp_ge_i32 s2, s88
	s_nop 0
	v_readfirstlane_b32 s8, v14
	s_cbranch_scc1 .LBB0_244
	v_lshlrev_b32_e32 v0, 4, v14
	v_add_u32_e32 v1, 0x2000, v0
	v_ashrrev_i32_e32 v2, 31, v1
	v_lshrrev_b32_e32 v2, 22, v2
	v_add_u32_e32 v2, v1, v2
	v_ashrrev_i32_e32 v8, 10, v2
	v_mul_i32_i24_e32 v2, 0x400, v8
	v_sub_u32_e32 v1, v1, v2
	s_ashr_i32 s9, s8, 6
	v_lshrrev_b32_e32 v2, 4, v1
	s_ashr_i32 s10, s8, 8
	s_lshl_b32 s34, s9, 10
	v_bitop3_b32 v1, v2, v1, 32 bitop3:0x6c
	s_and_b64 s[4:5], s[64:65], exec
	v_ashrrev_i32_e32 v2, 31, v1
	s_mov_b32 s5, 0x8400000
	v_lshrrev_b32_e32 v2, 26, v2
	s_mov_b32 s4, 0x600000
	s_cselect_b32 s5, s5, 0x9400000
	v_add_u32_e32 v2, v1, v2
	v_lshlrev_b32_e32 v3, 3, v8
	s_cselect_b32 s4, s4, 0x280000
	s_add_u32 s5, s78, s5
	v_ashrrev_i32_e32 v9, 6, v2
	v_and_b32_e32 v3, -16, v3
	s_addc_u32 s11, s79, 0
	s_mul_hi_i32 s13, s4, s98
	s_mul_i32 s4, s4, s98
	v_add_u32_e32 v3, v9, v3
	s_add_u32 s35, s5, s4
	v_and_b32_e32 v4, 3, v9
	s_mov_b32 s4, 0x1fffe0
	v_lshrrev_b32_e32 v5, 2, v3
	v_lshlrev_b32_e32 v6, 1, v3
	v_and_b32_e32 v2, 0xc0, v2
	v_and_or_b32 v4, v3, s4, v4
	v_and_b32_e32 v5, 4, v5
	v_and_b32_e32 v6, 24, v6
	v_sub_u32_e32 v1, v1, v2
	v_or3_b32 v4, v4, v5, v6
	v_lshlrev_b32_e32 v5, 5, v8
	v_ashrrev_i16_sdwa v1, v233, sext(v1) dst_sel:DWORD dst_unused:UNUSED_PAD src0_sel:DWORD src1_sel:BYTE_0
	v_and_b32_e32 v5, 32, v5
	v_bfe_i32 v10, v1, 0, 16
	v_add_lshl_u32 v1, v5, v10, 1
	v_lshl_add_u32 v128, v4, 11, v1
	v_lshl_add_u32 v130, v3, 11, v1
	v_bfe_i32 v1, v14, 27, 1
	v_lshrrev_b32_e32 v1, 22, v1
	v_add_u32_e32 v1, v0, v1
	v_and_b32_e32 v1, 0xfffffc00, v1
	v_sub_u32_e32 v0, v0, v1
	v_lshrrev_b32_e32 v1, 4, v0
	v_ashrrev_i32_e32 v2, 31, v14
	v_bitop3_b32 v0, v1, v0, 32 bitop3:0x6c
	v_lshrrev_b32_e32 v2, 26, v2
	v_ashrrev_i32_e32 v1, 31, v0
	v_add_u32_e32 v2, v14, v2
	v_lshrrev_b32_e32 v1, 26, v1
	v_ashrrev_i32_e32 v12, 6, v2
	v_add_u32_e32 v1, v0, v1
	v_lshlrev_b32_e32 v2, 3, v12
	v_ashrrev_i32_e32 v11, 6, v1
	v_and_b32_e32 v2, -16, v2
	v_add_u32_e32 v2, v11, v2
	v_and_b32_e32 v3, 3, v11
	v_and_or_b32 v3, v2, s4, v3
	v_readlane_b32 s4, v253, 63
	s_addc_u32 s48, s11, s13
	v_readlane_b32 s5, v254, 0
	s_and_b64 s[4:5], s[4:5], exec
	s_cselect_b32 s4, s27, s21
	v_readlane_b32 s5, v254, 1
	s_mul_i32 s4, s4, s5
	v_readlane_b32 s5, v254, 2
	s_add_i32 s4, s4, s5
	s_abs_i32 s11, s4
	s_mul_hi_u32 s13, s11, s28
	s_mul_i32 s14, s13, s20
	s_sub_i32 s11, s11, s14
	s_ashr_i32 s5, s4, 31
	s_add_i32 s14, s13, 1
	s_sub_i32 s15, s11, s20
	s_cmp_ge_u32 s11, s20
	s_cselect_b32 s13, s14, s13
	s_cselect_b32 s11, s15, s11
	s_add_i32 s14, s13, 1
	s_cmp_ge_u32 s11, s20
	s_cselect_b32 s11, s14, s13
	s_xor_b32 s11, s11, s5
	s_sub_i32 s5, s11, s5
	s_lshl_b32 s11, s5, 3
	v_and_b32_e32 v1, 0xc0, v1
	s_sub_i32 s13, 0x80, s11
	v_sub_u32_e32 v0, v0, v1
	s_min_i32 s13, s13, 8
	v_ashrrev_i16_sdwa v0, v233, sext(v0) dst_sel:DWORD dst_unused:UNUSED_PAD src0_sel:DWORD src1_sel:BYTE_0
	s_abs_i32 s14, s13
	v_bfe_i32 v13, v0, 0, 16
	v_cvt_f32_u32_e32 v0, s14
	s_sub_i32 s16, 0, s14
	s_mul_i32 s5, s5, s20
	s_sub_i32 s4, s4, s5
	v_rcp_iflag_f32_e32 v0, v0
	s_abs_i32 s15, s4
	s_xor_b32 s5, s4, s13
	s_ashr_i32 s5, s5, 31
	v_mul_f32_e32 v0, 0x4f7ffffe, v0
	v_cvt_u32_f32_e32 v0, v0
	v_lshrrev_b32_e32 v4, 2, v2
	v_lshlrev_b32_e32 v5, 1, v2
	v_and_b32_e32 v4, 4, v4
	v_readfirstlane_b32 s17, v0
	s_mul_i32 s16, s16, s17
	s_mul_hi_u32 s16, s17, s16
	s_add_i32 s17, s17, s16
	s_mul_hi_u32 s16, s15, s17
	s_mul_i32 s17, s16, s14
	s_sub_i32 s15, s15, s17
	s_add_i32 s17, s16, 1
	s_sub_i32 s18, s15, s14
	s_cmp_ge_u32 s15, s14
	s_cselect_b32 s16, s17, s16
	s_cselect_b32 s15, s18, s15
	s_add_i32 s17, s16, 1
	s_cmp_ge_u32 s15, s14
	s_cselect_b32 s14, s17, s16
	s_xor_b32 s14, s14, s5
	s_sub_i32 s40, s14, s5
	s_mul_i32 s5, s40, s13
	s_sub_i32 s4, s4, s5
	s_add_i32 s18, s4, s11
	v_and_b32_e32 v5, 24, v5
	s_ashr_i32 s19, s18, 31
	s_ashr_i32 s41, s40, 31
	v_or3_b32 v3, v3, v4, v5
	v_lshlrev_b32_e32 v4, 5, v12
	s_lshl_b64 s[4:5], s[18:19], 19
	s_lshl_b64 s[14:15], s[40:41], 19
	v_and_b32_e32 v4, 32, v4
	s_add_u32 s44, s35, s14
	v_add_lshl_u32 v1, v4, v13, 1
	s_addc_u32 s45, s48, s15
	s_add_i32 s49, s34, 0
	v_lshl_add_u32 v132, v3, 11, v1
	s_add_i32 m0, s49, 0x10000
	v_lshl_add_u32 v134, v2, 11, v1
	global_load_lds_dwordx4 v132, s[44:45]
	s_add_i32 m0, s49, 0x12000
	s_add_u32 s14, s44, 0x40000
	global_load_lds_dwordx4 v128, s[44:45]
	s_addc_u32 s15, s45, 0
	s_add_i32 m0, s49, 0x14000
	v_mov_b32_e32 v133, v157
	global_load_lds_dwordx4 v132, s[14:15]
	s_add_i32 m0, s49, 0x16000
	s_add_u32 s42, s0, s4
	s_addc_u32 s43, s1, s5
	s_add_i32 s50, s49, 0x2000
	global_load_lds_dwordx4 v128, s[14:15]
	s_mov_b32 m0, s49
	s_add_u32 s4, s42, 0x40000
	global_load_lds_dwordx4 v134, s[42:43]
	s_mov_b32 m0, s50
	s_addc_u32 s5, s43, 0
	s_add_i32 s51, s49, 0x4000
	global_load_lds_dwordx4 v130, s[42:43]
	s_mov_b32 m0, s51
	s_add_i32 s52, s49, 0x6000
	global_load_lds_dwordx4 v134, s[4:5]
	s_mov_b32 m0, s52
	v_mov_b32_e32 v129, v157
	global_load_lds_dwordx4 v130, s[4:5]
	v_mov_b32_e32 v135, v157
	v_mov_b32_e32 v131, v157
	s_cmp_eq_u32 s10, 1
	s_mov_b64 s[94:95], s[64:65]
	v_lshl_add_u64 v[6:7], s[44:45], 0, v[132:133]
	v_lshl_add_u64 v[4:5], s[44:45], 0, v[128:129]
	v_lshl_add_u64 v[0:1], s[42:43], 0, v[134:135]
	s_cselect_b64 s[4:5], -1, 0
	s_cmp_lg_u32 s10, 1
	v_lshl_add_u64 v[2:3], s[42:43], 0, v[130:131]
	s_setprio 1
	s_cbranch_scc1 .LBB0_231
	s_setprio 0
	s_barrier

; #define PG8_STAGE(bufoff, gbase, voff) do { _Pragma("unroll") for (int _i = 0; _i < 2; ++_i) \
;         __builtin_amdgcn_global_load_lds((const unsigned*)((const char*)(gbase) + (voff)[_i]), (PG8_LAS unsigned*)(lds + (bufoff) + ldsw + _i * 8192), 16, 0, 0); } while (0)
; #define PG8_BAR __builtin_amdgcn_s_barrier()
; template <class Epi, class Sched, bool ALIGN_EPI = false, bool SP2 = false>
; __device__ __forceinline__ void gemm_phase(PG8_LAS unsigned char* lds, const Gemm g, const Sched& S, const Epi& E) {
;     ...
;     const int tid = tid_, wid = __builtin_amdgcn_readfirstlane(tid >> 6), lane = tid & 63, wr = wid >> 2, wc = wid & 3, fr = lane & 15, fq = lane >> 4;
;     const int K = g.K, nt = K / BK;
;     unsigned voffA[2], voffB[2];
; #pragma unroll
;     for (int i = 0; i < 2; ++i) { int R, C; stage_rc(tid * 16 + i * 8192, R, C); const int Rb = Epi::PERM ? ((R & ~31) + perm32(R & 31)) : R;
;         voffA[i] = (unsigned)(R * K + C) * 2u; voffB[i] = (unsigned)(Rb * K + C) * 2u; }
;     ...
;     const char* cA = (const char*)g.A + (size_t)cur.pm * tstep; const char* cB = (const char*)g.Bt + (size_t)cur.pn * tstep;
;     S.a_ready(cur);
;     if constexpr (SP2) {
;         PG8_STAGE(PG8_SB(0, 0), cB, voffB); PG8_STAGE(PG8_SB(0, 1), cB + hstep, voffB); PG8_STAGE(PG8_SA(0, 0), cA, voffA); PG8_STAGE(PG8_SA(0, 1), cA + hstep, voffA);
;         if (wr == 1) PG8_BAR;
.LBB0_246:
	s_and_b64 vcc, exec, s[4:5]
	v_cmp_ne_u32_e64 s[38:39], 1, v231
	s_cbranch_vccz .LBB0_340
	s_waitcnt lgkmcnt(0)
	v_mov_b32_e32 v12, v230
	s_and_b64 vcc, exec, s[38:39]
	v_readfirstlane_b32 s6, v12
	s_cbranch_vccnz .LBB0_339
	s_cmp_lg_u32 s26, 1
	s_cselect_b64 s[4:5], -1, 0
	v_cndmask_b32_e64 v0, 0, 1, s[4:5]
	s_lshl_b32 s4, s25, 1
	v_readfirstlane_b32 s5, v0
	v_lshlrev_b32_e32 v0, 4, v12
	v_add_u32_e32 v1, 0x2000, v0
	v_ashrrev_i32_e32 v2, 31, v1
	v_lshrrev_b32_e32 v2, 22, v2
	v_add_u32_e32 v2, v1, v2
	v_ashrrev_i32_e32 v4, 10, v2
	v_mul_i32_i24_e32 v2, 0x400, v4
	v_sub_u32_e32 v1, v1, v2
	v_lshrrev_b32_e32 v2, 4, v1
	v_bitop3_b32 v1, v2, v1, 32 bitop3:0x6c
	v_ashrrev_i32_e32 v2, 31, v1
	v_lshrrev_b32_e32 v2, 26, v2
	s_or_b32 s4, s4, s5
	v_add_u32_e32 v2, v1, v2
	v_lshlrev_b32_e32 v3, 3, v4
	s_mul_hi_i32 s5, s4, 0x580000
	s_mul_i32 s4, s4, 0x580000
	v_ashrrev_i32_e32 v5, 6, v2
	v_and_b32_e32 v3, -16, v3
	s_add_u32 s18, s70, s4
	v_add_u32_e32 v3, v5, v3
	s_addc_u32 s19, s71, s5
	v_and_b32_e32 v6, 3, v5
	s_mov_b32 s5, 0xffffe0
	v_lshrrev_b32_e32 v7, 2, v3
	v_lshlrev_b32_e32 v8, 1, v3
	v_and_or_b32 v6, v3, s5, v6
	v_and_b32_e32 v7, 4, v7
	v_and_b32_e32 v8, 24, v8
	v_and_b32_e32 v2, 0xc0, v2
	v_or3_b32 v6, v6, v7, v8
	v_sub_u32_e32 v1, v1, v2
	v_mul_u32_u24_e32 v8, 0xb00, v6
	v_lshlrev_b32_e32 v6, 5, v4
	v_ashrrev_i16_sdwa v1, v233, sext(v1) dst_sel:DWORD dst_unused:UNUSED_PAD src0_sel:DWORD src1_sel:BYTE_0
	v_and_b32_e32 v6, 32, v6
	v_bfe_i32 v7, v1, 0, 16
	s_movk_i32 s4, 0xb00
	v_add_u32_e32 v1, v6, v7
	v_mul_lo_u32 v2, v3, s4
	v_add_lshl_u32 v170, v8, v1, 1
	v_add_lshl_u32 v172, v1, v2, 1
	v_bfe_i32 v1, v12, 27, 1
	v_lshrrev_b32_e32 v1, 22, v1
	v_add_u32_e32 v1, v0, v1
	v_and_b32_e32 v1, 0xfffffc00, v1
	v_sub_u32_e32 v0, v0, v1
	v_lshrrev_b32_e32 v1, 4, v0
	v_ashrrev_i32_e32 v2, 31, v12
	v_bitop3_b32 v0, v1, v0, 32 bitop3:0x6c
	v_lshrrev_b32_e32 v2, 26, v2
	v_ashrrev_i32_e32 v1, 31, v0
	v_add_u32_e32 v2, v12, v2
	v_lshrrev_b32_e32 v1, 26, v1
	v_ashrrev_i32_e32 v9, 6, v2
	v_add_u32_e32 v1, v0, v1
	v_lshlrev_b32_e32 v2, 3, v9
	v_ashrrev_i32_e32 v8, 6, v1
	v_and_b32_e32 v2, -16, v2
	v_add_u32_e32 v2, v8, v2
	v_and_b32_e32 v3, 3, v8
	v_lshrrev_b32_e32 v10, 2, v2
	v_lshlrev_b32_e32 v11, 1, v2
	v_and_b32_e32 v1, 0xc0, v1
	s_ashr_i32 s8, s6, 6
	v_and_or_b32 v3, v2, s5, v3
	v_and_b32_e32 v10, 4, v10
	v_and_b32_e32 v11, 24, v11
	v_sub_u32_e32 v0, v0, v1
	v_readlane_b32 s5, v254, 6
	s_ashr_i32 s7, s6, 8
	s_lshl_b32 s20, s8, 10
	v_or3_b32 v3, v3, v10, v11
	v_lshlrev_b32_e32 v10, 5, v9
	v_ashrrev_i16_sdwa v0, v233, sext(v0) dst_sel:DWORD dst_unused:UNUSED_PAD src0_sel:DWORD src1_sel:BYTE_0
	v_mul_lo_u32 v1, v2, s4
	s_mul_i32 s4, s5, 0x160000
	v_and_b32_e32 v10, 32, v10
	v_bfe_i32 v11, v0, 0, 16
	s_add_u32 s12, s18, s4
	s_mul_hi_i32 s4, s5, 0x160000
	v_mul_u32_u24_e32 v3, 0xb00, v3
	v_add_u32_e32 v0, v10, v11
	s_addc_u32 s13, s19, s4
	s_add_i32 s21, s20, 0
	v_add_lshl_u32 v156, v3, v0, 1
	s_add_i32 m0, s21, 0x10000
	v_add_lshl_u32 v174, v0, v1, 1
	global_load_lds_dwordx4 v156, s[12:13]
	s_add_i32 m0, s21, 0x12000
	s_add_u32 s4, s12, 0xb0000
	global_load_lds_dwordx4 v170, s[12:13]
	s_addc_u32 s5, s13, 0
	s_add_i32 m0, s21, 0x14000
	s_add_i32 s27, s21, 0x2000
	global_load_lds_dwordx4 v156, s[4:5]
	s_add_i32 m0, s21, 0x16000
	s_add_i32 s54, s21, 0x4000
	global_load_lds_dwordx4 v170, s[4:5]
	v_readlane_b32 s4, v254, 23
	s_mov_b32 m0, s21
	v_readlane_b32 s5, v254, 24
	s_add_i32 s55, s21, 0x6000
	v_mov_b32_e32 v171, v157
	s_cmp_eq_u32 s7, 1
	v_lshl_add_u64 v[0:1], s[12:13], 0, v[156:157]
	v_lshl_add_u64 v[2:3], s[12:13], 0, v[170:171]
	global_load_lds_dwordx4 v174, s[4:5]
	s_mov_b32 m0, s27
	s_nop 0
	global_load_lds_dwordx4 v172, s[4:5]
	v_readlane_b32 s4, v254, 25
	s_mov_b32 m0, s54
	v_readlane_b32 s5, v254, 26
	s_nop 4
	global_load_lds_dwordx4 v174, s[4:5]
	s_mov_b32 m0, s55
	s_nop 0
	global_load_lds_dwordx4 v172, s[4:5]
	s_cselect_b64 s[4:5], -1, 0
	s_cmp_lg_u32 s7, 1
	s_setprio 1
	s_cbranch_scc1 .LBB0_250
	s_setprio 0
	s_barrier

; #define PG8_STAGE(bufoff, gbase, voff) do { _Pragma("unroll") for (int _i = 0; _i < 2; ++_i) \
;         __builtin_amdgcn_global_load_lds((const unsigned*)((const char*)(gbase) + (voff)[_i]), (PG8_LAS unsigned*)(lds + (bufoff) + ldsw + _i * 8192), 16, 0, 0); } while (0)
; #define PG8_BAR __builtin_amdgcn_s_barrier()
; template <class Epi, class Sched, bool ALIGN_EPI = false, bool SP2 = false>
; __device__ __forceinline__ void gemm_phase(PG8_LAS unsigned char* lds, const Gemm g, const Sched& S, const Epi& E) {
;     ...
;     const int tid = tid_, wid = __builtin_amdgcn_readfirstlane(tid >> 6), lane = tid & 63, wr = wid >> 2, wc = wid & 3, fr = lane & 15, fq = lane >> 4;
;     const int K = g.K, nt = K / BK;
;     unsigned voffA[2], voffB[2];
; #pragma unroll
;     for (int i = 0; i < 2; ++i) { int R, C; stage_rc(tid * 16 + i * 8192, R, C); const int Rb = Epi::PERM ? ((R & ~31) + perm32(R & 31)) : R;
;         voffA[i] = (unsigned)(R * K + C) * 2u; voffB[i] = (unsigned)(Rb * K + C) * 2u; }
;     ...
;     const char* cA = (const char*)g.A + (size_t)cur.pm * tstep; const char* cB = (const char*)g.Bt + (size_t)cur.pn * tstep;
;     S.a_ready(cur);
;     if constexpr (SP2) {
;         PG8_STAGE(PG8_SB(0, 0), cB, voffB); PG8_STAGE(PG8_SB(0, 1), cB + hstep, voffB); PG8_STAGE(PG8_SA(0, 0), cA, voffA); PG8_STAGE(PG8_SA(0, 1), cA + hstep, voffA);
;         if (wr == 1) PG8_BAR;
.LBB0_342:
	v_readlane_b32 s94, v254, 57
	s_andn2_b64 vcc, exec, s[6:7]
	v_readlane_b32 s95, v254, 58
	s_cbranch_vccnz .LBB0_366
	v_mov_b32_e32 v10, v230
	s_and_b64 vcc, exec, s[38:39]
	v_readfirstlane_b32 s6, v10
	s_cbranch_vccnz .LBB0_365
	v_lshlrev_b32_e32 v0, 4, v10
	v_add_u32_e32 v1, 0x2000, v0
	v_ashrrev_i32_e32 v2, 31, v1
	v_lshrrev_b32_e32 v2, 22, v2
	v_add_u32_e32 v2, v1, v2
	v_ashrrev_i32_e32 v4, 10, v2
	v_mul_i32_i24_e32 v2, 0x400, v4
	v_sub_u32_e32 v1, v1, v2
	v_lshrrev_b32_e32 v2, 4, v1
	s_ashr_i32 s99, s98, 31
	v_bitop3_b32 v1, v2, v1, 32 bitop3:0x6c
	s_lshl_b64 s[4:5], s[98:99], 21
	v_ashrrev_i32_e32 v2, 31, v1
	s_and_b64 s[8:9], s[64:65], exec
	s_mov_b32 s7, 0x9000000
	v_lshrrev_b32_e32 v2, 26, v2
	s_cselect_b32 s7, s7, 0x9900000
	v_add_u32_e32 v2, v1, v2
	v_lshlrev_b32_e32 v3, 3, v4
	s_add_u32 s7, s78, s7
	s_waitcnt lgkmcnt(0)
	v_ashrrev_i32_e32 v5, 6, v2
	v_and_b32_e32 v3, -16, v3
	s_addc_u32 s8, s79, 0
	v_add_u32_e32 v3, v5, v3
	s_add_u32 s12, s7, s4
	v_and_b32_e32 v6, 3, v5
	s_mov_b32 s4, 0x1fffe0
	v_lshrrev_b32_e32 v7, 2, v3
	v_lshlrev_b32_e32 v8, 1, v3
	v_and_b32_e32 v2, 0xc0, v2
	v_and_or_b32 v6, v3, s4, v6
	v_and_b32_e32 v7, 4, v7
	v_and_b32_e32 v8, 24, v8
	v_sub_u32_e32 v1, v1, v2
	v_or3_b32 v7, v6, v7, v8
	v_lshlrev_b32_e32 v6, 5, v4
	v_ashrrev_i16_sdwa v1, v233, sext(v1) dst_sel:DWORD dst_unused:UNUSED_PAD src0_sel:DWORD src1_sel:BYTE_0
	v_and_b32_e32 v8, 32, v6
	v_bfe_i32 v6, v1, 0, 16
	v_add_lshl_u32 v1, v8, v6, 1
	v_lshl_add_u32 v170, v7, 11, v1
	v_lshl_add_u32 v172, v3, 11, v1
	v_bfe_i32 v1, v10, 27, 1
	v_lshrrev_b32_e32 v1, 22, v1
	v_add_u32_e32 v1, v0, v1
	v_and_b32_e32 v1, 0xfffffc00, v1
	v_sub_u32_e32 v0, v0, v1
	v_lshrrev_b32_e32 v1, 4, v0
	v_ashrrev_i32_e32 v2, 31, v10
	v_bitop3_b32 v0, v1, v0, 32 bitop3:0x6c
	v_lshrrev_b32_e32 v2, 26, v2
	v_ashrrev_i32_e32 v1, 31, v0
	v_add_u32_e32 v2, v10, v2
	v_lshrrev_b32_e32 v1, 26, v1
	v_ashrrev_i32_e32 v8, 6, v2
	v_add_u32_e32 v1, v0, v1
	v_lshlrev_b32_e32 v2, 3, v8
	v_ashrrev_i32_e32 v7, 6, v1
	v_and_b32_e32 v2, -16, v2
	v_add_u32_e32 v2, v7, v2
	v_and_b32_e32 v3, 3, v7
	v_lshrrev_b32_e32 v9, 2, v2
	v_lshlrev_b32_e32 v11, 1, v2
	v_and_b32_e32 v1, 0xc0, v1
	s_addc_u32 s13, s8, s5
	s_ashr_i32 s10, s6, 6
	v_and_or_b32 v3, v2, s4, v3
	v_and_b32_e32 v9, 4, v9
	v_and_b32_e32 v11, 24, v11
	v_sub_u32_e32 v0, v0, v1
	s_ashr_i32 s7, s6, 8
	s_lshl_b32 s14, s10, 10
	v_or3_b32 v3, v3, v9, v11
	v_lshlrev_b32_e32 v9, 5, v8
	v_ashrrev_i16_sdwa v0, v233, sext(v0) dst_sel:DWORD dst_unused:UNUSED_PAD src0_sel:DWORD src1_sel:BYTE_0
	v_readlane_b32 s4, v254, 13
	v_and_b32_e32 v11, 32, v9
	v_bfe_i32 v9, v0, 0, 16
	v_readlane_b32 s5, v254, 14
	s_add_u32 s8, s12, s4
	v_add_lshl_u32 v0, v11, v9, 1
	s_addc_u32 s9, s13, s5
	s_add_i32 s15, s14, 0
	v_lshl_add_u32 v156, v3, 11, v0
	s_add_i32 m0, s15, 0x10000
	v_lshl_add_u32 v174, v2, 11, v0
	global_load_lds_dwordx4 v156, s[8:9]
	s_add_i32 m0, s15, 0x12000
	s_add_u32 s4, s8, 0x40000
	global_load_lds_dwordx4 v170, s[8:9]
	s_addc_u32 s5, s9, 0
	s_add_i32 m0, s15, 0x14000
	s_add_i32 s16, s15, 0x2000
	global_load_lds_dwordx4 v156, s[4:5]
	s_add_i32 m0, s15, 0x16000
	s_add_i32 s17, s15, 0x4000
	global_load_lds_dwordx4 v170, s[4:5]
	v_readlane_b32 s4, v254, 17
	s_mov_b32 m0, s15
	v_readlane_b32 s5, v254, 18
	s_add_i32 s18, s15, 0x6000
	v_mov_b32_e32 v171, v157
	s_cmp_eq_u32 s7, 1
	v_lshl_add_u64 v[0:1], s[8:9], 0, v[156:157]
	v_lshl_add_u64 v[2:3], s[8:9], 0, v[170:171]
	global_load_lds_dwordx4 v174, s[4:5]
	s_mov_b32 m0, s16
	s_nop 0
	global_load_lds_dwordx4 v172, s[4:5]
	v_readlane_b32 s4, v254, 19
	s_mov_b32 m0, s17
	v_readlane_b32 s5, v254, 20
	s_nop 4
	global_load_lds_dwordx4 v174, s[4:5]
	s_mov_b32 m0, s18
	s_nop 0
	global_load_lds_dwordx4 v172, s[4:5]
	s_cselect_b64 s[4:5], -1, 0
	s_cmp_lg_u32 s7, 1
	s_setprio 1
	s_cbranch_scc1 .LBB0_346
	s_setprio 0
	s_barrier

; #define PG8_STAGE(bufoff, gbase, voff) do { _Pragma("unroll") for (int _i = 0; _i < 2; ++_i) \
;         __builtin_amdgcn_global_load_lds((const unsigned*)((const char*)(gbase) + (voff)[_i]), (PG8_LAS unsigned*)(lds + (bufoff) + ldsw + _i * 8192), 16, 0, 0); } while (0)
; #define PG8_BAR __builtin_amdgcn_s_barrier()
; template <class Epi, class Sched, bool ALIGN_EPI = false, bool SP2 = false>
; __device__ __forceinline__ void gemm_phase(PG8_LAS unsigned char* lds, const Gemm g, const Sched& S, const Epi& E) {
;     ...
;     const int tid = tid_, wid = __builtin_amdgcn_readfirstlane(tid >> 6), lane = tid & 63, wr = wid >> 2, wc = wid & 3, fr = lane & 15, fq = lane >> 4;
;     const int K = g.K, nt = K / BK;
;     unsigned voffA[2], voffB[2];
; #pragma unroll
;     for (int i = 0; i < 2; ++i) { int R, C; stage_rc(tid * 16 + i * 8192, R, C); const int Rb = Epi::PERM ? ((R & ~31) + perm32(R & 31)) : R;
;         voffA[i] = (unsigned)(R * K + C) * 2u; voffB[i] = (unsigned)(Rb * K + C) * 2u; }
;     ...
;     const char* cA = (const char*)g.A + (size_t)cur.pm * tstep; const char* cB = (const char*)g.Bt + (size_t)cur.pn * tstep;
;     S.a_ready(cur);
;     if constexpr (SP2) {
;         PG8_STAGE(PG8_SB(0, 0), cB, voffB); PG8_STAGE(PG8_SB(0, 1), cB + hstep, voffB); PG8_STAGE(PG8_SA(0, 0), cA, voffA); PG8_STAGE(PG8_SA(0, 1), cA + hstep, voffA);
;         if (wr == 1) PG8_BAR;
.LBB0_390:
	v_readlane_b32 s4, v253, 9
	v_mov_b32_e32 v4, v230
	v_readlane_b32 s5, v253, 10
	s_waitcnt vmcnt(0) lgkmcnt(0)
	s_barrier
	s_andn2_b64 vcc, exec, s[4:5]
	v_readfirstlane_b32 s6, v4
	s_cbranch_vccnz .LBB0_406
	s_cmp_lg_u32 s26, 0
	s_cselect_b64 s[4:5], -1, 0
	v_cndmask_b32_e64 v0, 0, 1, s[4:5]
	s_lshl_b32 s4, s25, 1
	v_readfirstlane_b32 s5, v0
	v_lshlrev_b32_e32 v0, 4, v4
	v_add_u32_e32 v1, 0x2000, v0
	v_ashrrev_i32_e32 v2, 31, v1
	v_lshrrev_b32_e32 v2, 22, v2
	v_add_u32_e32 v2, v1, v2
	v_ashrrev_i32_e32 v5, 10, v2
	v_mul_i32_i24_e32 v2, 0x400, v5
	v_sub_u32_e32 v1, v1, v2
	v_lshrrev_b32_e32 v2, 4, v1
	v_bitop3_b32 v1, v2, v1, 32 bitop3:0x6c
	v_ashrrev_i32_e32 v2, 31, v1
	v_lshrrev_b32_e32 v2, 26, v2
	v_add_u32_e32 v2, v1, v2
	v_lshlrev_b32_e32 v3, 3, v5
	s_or_b32 s4, s4, s5
	v_ashrrev_i32_e32 v6, 6, v2
	v_and_b32_e32 v3, -16, v3
	s_mul_hi_i32 s5, s4, 0xb00000
	s_mul_i32 s4, s4, 0xb00000
	v_add_u32_e32 v3, v6, v3
	s_add_u32 s19, s78, s4
	v_and_b32_e32 v7, 3, v6
	s_mov_b32 s4, 0x1fffe0
	v_lshrrev_b32_e32 v8, 2, v3
	v_lshlrev_b32_e32 v9, 1, v3
	v_and_b32_e32 v2, 0xc0, v2
	v_and_or_b32 v7, v3, s4, v7
	v_and_b32_e32 v8, 4, v8
	v_and_b32_e32 v9, 24, v9
	v_sub_u32_e32 v1, v1, v2
	v_or3_b32 v8, v7, v8, v9
	v_lshlrev_b32_e32 v7, 5, v5
	v_ashrrev_i16_sdwa v1, v233, sext(v1) dst_sel:DWORD dst_unused:UNUSED_PAD src0_sel:DWORD src1_sel:BYTE_0
	v_and_b32_e32 v9, 32, v7
	v_bfe_i32 v7, v1, 0, 16
	v_add_lshl_u32 v1, v9, v7, 1
	v_lshl_add_u32 v128, v8, 11, v1
	v_lshl_add_u32 v130, v3, 11, v1
	v_bfe_i32 v1, v4, 27, 1
	v_lshrrev_b32_e32 v1, 22, v1
	v_add_u32_e32 v1, v0, v1
	v_and_b32_e32 v1, 0xfffffc00, v1
	v_sub_u32_e32 v0, v0, v1
	v_lshrrev_b32_e32 v1, 4, v0
	v_ashrrev_i32_e32 v2, 31, v4
	v_bitop3_b32 v0, v1, v0, 32 bitop3:0x6c
	v_lshrrev_b32_e32 v2, 26, v2
	v_ashrrev_i32_e32 v1, 31, v0
	v_add_u32_e32 v2, v4, v2
	v_lshrrev_b32_e32 v1, 26, v1
	v_ashrrev_i32_e32 v9, 6, v2
	v_add_u32_e32 v1, v0, v1
	v_lshlrev_b32_e32 v2, 3, v9
	v_ashrrev_i32_e32 v8, 6, v1
	v_and_b32_e32 v2, -16, v2
	v_add_u32_e32 v2, v8, v2
	v_and_b32_e32 v3, 3, v8
	v_lshrrev_b32_e32 v10, 2, v2
	v_lshlrev_b32_e32 v11, 1, v2
	v_and_b32_e32 v1, 0xc0, v1
	s_addc_u32 s20, s79, s5
	s_ashr_i32 s7, s6, 6
	v_and_or_b32 v3, v2, s4, v3
	v_and_b32_e32 v10, 4, v10
	v_and_b32_e32 v11, 24, v11
	v_sub_u32_e32 v0, v0, v1
	s_ashr_i32 s8, s6, 8
	s_lshl_b32 s21, s7, 10
	v_or3_b32 v3, v3, v10, v11
	v_lshlrev_b32_e32 v10, 5, v9
	v_ashrrev_i16_sdwa v0, v233, sext(v0) dst_sel:DWORD dst_unused:UNUSED_PAD src0_sel:DWORD src1_sel:BYTE_0
	v_readlane_b32 s4, v254, 4
	v_and_b32_e32 v11, 32, v10
	v_bfe_i32 v10, v0, 0, 16
	v_readlane_b32 s5, v254, 5
	s_add_u32 s12, s19, s4
	v_add_lshl_u32 v0, v11, v10, 1
	s_addc_u32 s13, s20, s5
	s_add_i32 s25, s21, 0
	v_lshl_add_u32 v156, v3, 11, v0
	s_add_i32 m0, s25, 0x10000
	v_lshl_add_u32 v132, v2, 11, v0
	global_load_lds_dwordx4 v156, s[12:13]
	s_add_i32 m0, s25, 0x12000
	s_add_u32 s4, s12, 0x40000
	global_load_lds_dwordx4 v128, s[12:13]
	s_addc_u32 s5, s13, 0
	s_add_i32 m0, s25, 0x14000
	s_add_i32 s26, s25, 0x2000
	global_load_lds_dwordx4 v156, s[4:5]
	s_add_i32 m0, s25, 0x16000
	s_add_i32 s27, s25, 0x4000
	global_load_lds_dwordx4 v128, s[4:5]
	v_readlane_b32 s4, v254, 9
	s_mov_b32 m0, s25
	v_readlane_b32 s5, v254, 10
	s_add_i32 s28, s25, 0x6000
	v_mov_b32_e32 v129, v157
	s_cmp_eq_u32 s8, 1
	v_lshl_add_u64 v[0:1], s[12:13], 0, v[156:157]
	v_lshl_add_u64 v[2:3], s[12:13], 0, v[128:129]
	global_load_lds_dwordx4 v132, s[4:5]
	s_mov_b32 m0, s26
	s_nop 0
	global_load_lds_dwordx4 v130, s[4:5]
	v_readlane_b32 s4, v254, 11
	s_mov_b32 m0, s27
	v_readlane_b32 s5, v254, 12
	s_nop 4
	global_load_lds_dwordx4 v132, s[4:5]
	s_mov_b32 m0, s28
	s_nop 0
	global_load_lds_dwordx4 v130, s[4:5]
	s_cselect_b64 s[4:5], -1, 0
	s_cmp_lg_u32 s8, 1
	s_setprio 1
	s_cbranch_scc1 .LBB0_393
	s_setprio 0
	s_barrier
